# attention steps: removed redundant issue slots (m0 save/restore around LDS-DMA, no-op lgkmcnt waits before QK MFMAs, s_nop between empty asm markers)
# speedup vs baseline: 1.0258x; 1.0055x over previous
.LBB0_146:
	v_lshlrev_b32_e32 v34, 1, v32
	v_lshrrev_b32_e32 v32, 2, v32
	v_and_b32_e32 v215, 32, v34
	v_and_or_b32 v32, v32, 3, v218
	v_lshlrev_b32_e32 v214, 6, v32
	v_add_u32_e32 v32, 0, v215
	v_add3_u32 v221, v32, v213, v214
	v_max3_f32 v32, v0, v1, v16
	v_max3_f32 v34, v2, v3, v17
	s_and_b32 s5, s5, 0x3fffffc0
	v_max3_f32 v32, v32, v18, v19
	v_max3_f32 v34, v34, v6, v7
	s_lshl_b32 s5, s5, 2
	v_max3_f32 v32, v32, v4, v5
	v_max3_f32 v34, v34, v22, v23
	s_add_i32 s6, s5, 0
	v_max3_f32 v32, v32, v20, v21
	v_max3_f32 v34, v34, v10, v11
	s_cmp_lg_u32 0, -1
	v_max3_f32 v32, v32, v8, v9
	v_max3_f32 v34, v34, v26, v27
	s_mov_b64 s[14:15], 0x20000
	v_max3_f32 v32, v32, v24, v25
	v_max3_f32 v34, v34, v14, v15
	s_mov_b32 s36, 1
	v_max3_f32 v32, v32, v12, v13
	v_max3_f32 v34, v34, v30, v31
	s_mov_b32 s28, 0
	v_max3_f32 v32, v32, v28, v29
	v_lshl_add_u32 v217, v211, 2, s6
	v_max_f32_e32 v32, v32, v34
	v_lshl_add_u32 v216, v218, 2, s6
	v_mov_b32_e32 v34, v32
	s_nop 1
	v_permlane32_swap_b32_e32 v32, v34
	v_max_f32_e32 v32, v32, v34
	s_nop 0
	v_sub_f32_e32 v0, v0, v32
	v_sub_f32_e32 v1, v1, v32
	v_sub_f32_e32 v2, v2, v32
	v_sub_f32_e32 v3, v3, v32
	v_sub_f32_e32 v4, v4, v32
	v_sub_f32_e32 v5, v5, v32
	v_sub_f32_e32 v6, v6, v32
	v_sub_f32_e32 v7, v7, v32
	v_sub_f32_e32 v8, v8, v32
	v_sub_f32_e32 v9, v9, v32
	v_sub_f32_e32 v10, v10, v32
	v_sub_f32_e32 v11, v11, v32
	v_sub_f32_e32 v12, v12, v32
	v_sub_f32_e32 v13, v13, v32
	v_sub_f32_e32 v14, v14, v32
	v_sub_f32_e32 v15, v15, v32
	v_sub_f32_e32 v34, v16, v32
	v_sub_f32_e32 v35, v17, v32
	v_sub_f32_e32 v36, v18, v32
	v_sub_f32_e32 v37, v19, v32
	v_sub_f32_e32 v38, v20, v32
	v_sub_f32_e32 v39, v21, v32
	v_sub_f32_e32 v40, v22, v32
	v_sub_f32_e32 v41, v23, v32
	v_sub_f32_e32 v42, v24, v32
	v_sub_f32_e32 v43, v25, v32
	v_sub_f32_e32 v44, v26, v32
	v_sub_f32_e32 v45, v27, v32
	v_sub_f32_e32 v46, v28, v32
	v_sub_f32_e32 v47, v29, v32
	v_sub_f32_e32 v48, v30, v32
	v_sub_f32_e32 v49, v31, v32
	s_nop 0
	v_exp_f32_e32 v80, v0
	v_exp_f32_e32 v81, v1
	v_exp_f32_e32 v82, v2
	v_exp_f32_e32 v83, v3
	v_exp_f32_e32 v84, v4
	v_exp_f32_e32 v85, v5
	v_exp_f32_e32 v86, v6
	v_exp_f32_e32 v87, v7
	v_exp_f32_e32 v88, v8
	v_exp_f32_e32 v89, v9
	v_exp_f32_e32 v90, v10
	v_exp_f32_e32 v91, v11
	v_exp_f32_e32 v92, v12
	v_exp_f32_e32 v93, v13
	v_exp_f32_e32 v94, v14
	v_exp_f32_e32 v95, v15
	ds_read_b128 v[0:3], v33 offset:256
	ds_read_b128 v[4:7], v33 offset:288
	ds_read_b128 v[8:11], v33 offset:384
	ds_read_b128 v[12:15], v33 offset:416
	ds_read_b128 v[16:19], v33 offset:320
	ds_read_b128 v[20:23], v33 offset:352
	ds_read_b128 v[24:27], v33 offset:448
	ds_read_b128 v[28:31], v33 offset:480
	s_waitcnt vmcnt(0) lgkmcnt(0)
	s_barrier
	v_add_f32_e32 v204, v193, v32
	v_exp_f32_e32 v32, v34
	s_waitcnt lgkmcnt(7)
	v_sub_f32_e32 v65, v1, v204
	v_sub_f32_e32 v64, v0, v204
	v_lshl_add_u64 v[0:1], v[206:207], 0, s[48:49]
	s_mov_b32 m0, s18
	s_nop 0
	global_load_lds_dwordx4 v[0:1], off
	s_cselect_b32 s5, 0, 0
	s_add_i32 s4, s5, s4
	v_lshl_add_u64 v[0:1], v[208:209], 0, s[14:15]
	s_add_i32 s4, s4, 0x8000
	s_mov_b32 m0, s4
	s_nop 0
	global_load_lds_dwordx4 v[0:1], off
	ds_read_b128 v[156:159], v220 offset:8192
	ds_read_b128 v[152:155], v220 offset:8704
	ds_read_b128 v[148:151], v220 offset:10240
	ds_read_b128 v[144:147], v220 offset:10752
	ds_read_b128 v[140:143], v220 offset:12288
	ds_read_b128 v[132:135], v220 offset:12800
	ds_read_b128 v[136:139], v220 offset:14336
	ds_read_b128 v[128:131], v220 offset:14848
	v_exp_f32_e32 v33, v35
	v_exp_f32_e32 v34, v36
	v_exp_f32_e32 v35, v37
	v_exp_f32_e32 v36, v38
	v_exp_f32_e32 v37, v39
	v_exp_f32_e32 v38, v40
	v_exp_f32_e32 v39, v41
	v_exp_f32_e32 v40, v42
	v_exp_f32_e32 v41, v43
	v_exp_f32_e32 v42, v44
	v_exp_f32_e32 v43, v45
	v_exp_f32_e32 v44, v46
	v_exp_f32_e32 v45, v47
	v_exp_f32_e32 v46, v48
	v_exp_f32_e32 v47, v49
	s_waitcnt vmcnt(2) lgkmcnt(0)
	s_barrier
	s_waitcnt lgkmcnt(10)
	v_sub_f32_e32 v79, v23, v204
	v_sub_f32_e32 v78, v22, v204
	v_sub_f32_e32 v77, v21, v204
	v_sub_f32_e32 v76, v20, v204
	v_sub_f32_e32 v75, v19, v204
	v_sub_f32_e32 v74, v18, v204
	v_sub_f32_e32 v73, v17, v204
	v_sub_f32_e32 v72, v16, v204
	v_sub_f32_e32 v71, v7, v204
	v_sub_f32_e32 v70, v6, v204
	v_sub_f32_e32 v69, v5, v204
	v_sub_f32_e32 v68, v4, v204
	v_sub_f32_e32 v67, v3, v204
	v_sub_f32_e32 v66, v2, v204
	s_waitcnt lgkmcnt(8)
	v_sub_f32_e32 v63, v31, v204
	v_sub_f32_e32 v62, v30, v204
	v_sub_f32_e32 v61, v29, v204
	v_sub_f32_e32 v60, v28, v204
	v_sub_f32_e32 v59, v27, v204
	v_sub_f32_e32 v58, v26, v204
	v_sub_f32_e32 v57, v25, v204
	v_sub_f32_e32 v56, v24, v204
	v_sub_f32_e32 v55, v15, v204
	v_sub_f32_e32 v54, v14, v204
	v_sub_f32_e32 v53, v13, v204
	v_sub_f32_e32 v52, v12, v204
	v_sub_f32_e32 v51, v11, v204
	v_sub_f32_e32 v50, v10, v204
	v_sub_f32_e32 v49, v9, v204
	v_sub_f32_e32 v48, v8, v204
	s_cmp_lt_i32 s20, 7
	v_cmp_gt_u32_e64 s[4:5], 32, v197
	s_cbranch_scc1 .LBB0_165
	s_add_i32 s6, s17, 0
	s_add_i32 s6, s6, 0x14a00
	v_mov_b32_e32 v16, v193
	v_mov_b32_e32 v17, v193
	v_lshl_add_u32 v180, v212, 4, s6
	s_mov_b64 s[6:7], 0xa0000
	v_mov_b32_e32 v18, v193
	v_mov_b32_e32 v19, v193
	v_mov_b32_e32 v20, v193
	v_mov_b32_e32 v21, v193
	v_mov_b32_e32 v22, v193
	v_mov_b32_e32 v23, v193
	v_mov_b32_e32 v24, v193
	v_mov_b32_e32 v25, v193
	v_mov_b32_e32 v26, v193
	v_mov_b32_e32 v27, v193
	v_mov_b32_e32 v28, v193
	v_mov_b32_e32 v29, v193
	v_mov_b32_e32 v30, v193
	v_mov_b32_e32 v31, v193
	v_mov_b64_e32 v[0:1], v[16:17]
	v_lshl_add_u64 v[176:177], v[208:209], 0, s[48:49]
	v_lshl_add_u64 v[178:179], v[206:207], 0, s[6:7]
	s_mov_b32 s6, 0
	s_movk_i32 s28, 0x4000
	s_movk_i32 s41, 0x2000
	v_mov_b32_e32 v222, 0
	s_mov_b32 s36, 6
	v_mov_b64_e32 v[2:3], v[18:19]
	v_mov_b64_e32 v[4:5], v[20:21]
	v_mov_b64_e32 v[6:7], v[22:23]
	v_mov_b64_e32 v[8:9], v[24:25]
	v_mov_b64_e32 v[10:11], v[26:27]
	v_mov_b64_e32 v[12:13], v[28:29]
	v_mov_b64_e32 v[14:15], v[30:31]
.LBB0_148:
	v_add_u32_e32 v168, s6, v221
	ds_read_b64_tr_b16 v[164:165], v168 offset:24576
	ds_read_b64_tr_b16 v[166:167], v168 offset:25088
	v_mfma_f32_32x32x16_bf16 v[64:79], v[156:159], v[116:119], v[64:79]
	v_add_f32_e32 v104, v80, v81
	v_add_f32_e32 v104, v82, v104
	v_add_f32_e32 v104, v83, v104
	v_add_f32_e32 v104, v84, v104
	v_add_f32_e32 v104, v85, v104
	v_cvt_pk_bf16_f32 v124, v80, v81
	v_cvt_pk_bf16_f32 v125, v82, v83
	ds_read_b64_tr_b16 v[160:161], v168 offset:28672
	ds_read_b64_tr_b16 v[162:163], v168 offset:29184
	v_mfma_f32_32x32x16_bf16 v[48:63], v[152:155], v[116:119], v[48:63]
	v_add_f32_e32 v80, v86, v104
	v_add_f32_e32 v80, v87, v80
	v_add_f32_e32 v80, v88, v80
	v_add_f32_e32 v80, v89, v80
	v_cvt_pk_bf16_f32 v126, v84, v85
	v_cvt_pk_bf16_f32 v127, v86, v87
	ds_read_b64_tr_b16 v[152:153], v168 offset:25600
	ds_read_b64_tr_b16 v[154:155], v168 offset:26112
	v_mfma_f32_32x32x16_bf16 v[64:79], v[148:151], v[108:111], v[64:79]
	v_add_f32_e32 v80, v90, v80
	v_add_f32_e32 v80, v91, v80
	v_add_f32_e32 v80, v92, v80
	v_add_f32_e32 v80, v93, v80
	v_cvt_pk_bf16_f32 v120, v88, v89
	v_cvt_pk_bf16_f32 v121, v90, v91
	ds_read_b64_tr_b16 v[148:149], v168 offset:29696
	ds_read_b64_tr_b16 v[150:151], v168 offset:30208
	v_mfma_f32_32x32x16_bf16 v[48:63], v[144:147], v[108:111], v[48:63]
	v_add_f32_e32 v80, v94, v80
	v_add_f32_e32 v80, v95, v80
	v_add_f32_e32 v80, v32, v80
	v_add_f32_e32 v80, v33, v80
	v_cvt_pk_bf16_f32 v122, v92, v93
	v_cvt_pk_bf16_f32 v123, v94, v95
	ds_read_b64_tr_b16 v[156:157], v168 offset:26624
	ds_read_b64_tr_b16 v[158:159], v168 offset:27136
	v_mfma_f32_32x32x16_bf16 v[64:79], v[140:143], v[100:103], v[64:79]
	v_add_f32_e32 v80, v34, v80
	v_add_f32_e32 v80, v35, v80
	v_add_f32_e32 v80, v36, v80
	v_add_f32_e32 v80, v37, v80
	v_cvt_pk_bf16_f32 v112, v32, v33
	v_cvt_pk_bf16_f32 v113, v34, v35
	ds_read_b64_tr_b16 v[144:145], v168 offset:30720
	ds_read_b64_tr_b16 v[146:147], v168 offset:31232
	v_mfma_f32_32x32x16_bf16 v[48:63], v[132:135], v[100:103], v[48:63]
	v_add_f32_e32 v32, v38, v80
	v_add_f32_e32 v32, v39, v32
	v_add_f32_e32 v32, v40, v32
	v_add_f32_e32 v32, v41, v32
	v_cvt_pk_bf16_f32 v114, v36, v37
	v_cvt_pk_bf16_f32 v115, v38, v39
	ds_read_b64_tr_b16 v[140:141], v168 offset:27648
	ds_read_b64_tr_b16 v[142:143], v168 offset:28160
	v_mfma_f32_32x32x16_bf16 v[64:79], v[136:139], v[96:99], v[64:79]
	v_add_f32_e32 v32, v42, v32
	v_add_f32_e32 v32, v43, v32
	v_add_f32_e32 v32, v44, v32
	v_add_f32_e32 v32, v45, v32
	v_cvt_pk_bf16_f32 v104, v40, v41
	v_cvt_pk_bf16_f32 v105, v42, v43
	ds_read_b64_tr_b16 v[132:133], v168 offset:31744
	ds_read_b64_tr_b16 v[134:135], v168 offset:32256
	v_mfma_f32_32x32x16_bf16 v[48:63], v[128:131], v[96:99], v[48:63]
	v_add_f32_e32 v32, v46, v32
	v_add_f32_e32 v32, v47, v32
	v_add_f32_e32 v34, 0, v32
	v_cvt_pk_bf16_f32 v106, v44, v45
	v_cvt_pk_bf16_f32 v107, v46, v47
	v_lshl_add_u64 v[32:33], v[178:179], 0, s[90:91]
	s_add_i32 s6, s41, s18
	s_mov_b32 m0, s6
	s_nop 0
	global_load_lds_dwordx4 v[32:33], off
	v_lshl_add_u64 v[32:33], v[176:177], 0, s[90:91]
	s_add_i32 s6, s28, s19
	s_mov_b32 m0, s6
	s_nop 0
	global_load_lds_dwordx4 v[32:33], off
	v_max_f32_e32 v32, v65, v65
	v_max_f32_e32 v33, v64, v64
	v_max_f32_e32 v32, v33, v32
	v_max3_f32 v33, v66, v67, v49
	v_max3_f32 v32, v32, v48, v50
	v_max3_f32 v32, v32, v51, v68
	v_max3_f32 v33, v33, v70, v71
	v_max3_f32 v32, v32, v69, v52
	v_max3_f32 v33, v33, v54, v55
	v_max3_f32 v32, v32, v53, v72
	v_max3_f32 v33, v33, v74, v75
	v_max3_f32 v32, v32, v73, v56
	v_max3_f32 v33, v33, v58, v59
	v_max3_f32 v32, v32, v57, v76
	v_max3_f32 v33, v33, v78, v79
	v_max3_f32 v32, v32, v77, v60
	v_max3_f32 v33, v33, v62, v63
	v_max3_f32 v32, v32, v61, v33
	v_mov_b32_e32 v33, v32
	s_nop 1
	v_permlane32_swap_b32_e32 v32, v33
	v_max_f32_e32 v33, v33, v33
	v_max_f32_e32 v32, v32, v32
	v_max_f32_e32 v32, v32, v33
	v_cmp_lt_f32_e32 vcc, s47, v32
	s_cmp_lg_u64 vcc, 0
	v_add_f32_e32 v181, v222, v34
	s_cselect_b64 s[6:7], -1, 0
	s_cbranch_vccnz .LBB0_156
.LBB0_149:
	ds_read_b128 v[32:35], v180
	ds_read_b128 v[84:87], v180 offset:32
	ds_read_b128 v[136:139], v180 offset:128
	ds_read_b128 v[36:39], v180 offset:160
	ds_read_b128 v[88:91], v180 offset:64
	ds_read_b128 v[92:95], v180 offset:96
	ds_read_b128 v[40:43], v180 offset:192
	ds_read_b128 v[44:47], v180 offset:224
	s_waitcnt lgkmcnt(14)
	v_mfma_f32_32x32x16_bf16 v[16:31], v[124:127], v[164:167], v[16:31]
	v_exp_f32_e32 v64, v64
	v_exp_f32_e32 v65, v65
	v_exp_f32_e32 v66, v66
	v_exp_f32_e32 v67, v67
	s_waitcnt lgkmcnt(7)
	v_pk_add_f32 v[80:81], v[32:33], v[204:205] op_sel_hi:[1,0] neg_lo:[0,1] neg_hi:[0,1]
	v_pk_add_f32 v[82:83], v[34:35], v[204:205] op_sel_hi:[1,0] neg_lo:[0,1] neg_hi:[0,1]
	s_waitcnt lgkmcnt(2)
	v_mfma_f32_32x32x16_bf16 v[0:15], v[124:127], v[160:163], v[0:15]
	v_exp_f32_e32 v68, v68
	v_exp_f32_e32 v69, v69
	v_exp_f32_e32 v70, v70
	v_exp_f32_e32 v71, v71
	v_pk_add_f32 v[84:85], v[84:85], v[204:205] op_sel_hi:[1,0] neg_lo:[0,1] neg_hi:[0,1]
	v_pk_add_f32 v[86:87], v[86:87], v[204:205] op_sel_hi:[1,0] neg_lo:[0,1] neg_hi:[0,1]
	v_add_u32_e32 v124, s28, v220
	ds_read_b128 v[168:171], v124
	ds_read_b128 v[128:131], v124 offset:512
	v_mfma_f32_32x32x16_bf16 v[16:31], v[120:123], v[152:155], v[16:31]
	v_exp_f32_e32 v72, v72
	v_exp_f32_e32 v73, v73
	v_exp_f32_e32 v74, v74
	v_exp_f32_e32 v75, v75
	v_pk_add_f32 v[88:89], v[88:89], v[204:205] op_sel_hi:[1,0] neg_lo:[0,1] neg_hi:[0,1]
	v_pk_add_f32 v[90:91], v[90:91], v[204:205] op_sel_hi:[1,0] neg_lo:[0,1] neg_hi:[0,1]
	ds_read_b128 v[164:167], v124 offset:2048
	ds_read_b128 v[152:155], v124 offset:2560
	v_mfma_f32_32x32x16_bf16 v[0:15], v[120:123], v[148:151], v[0:15]
	v_exp_f32_e32 v76, v76
	v_exp_f32_e32 v77, v77
	v_exp_f32_e32 v78, v78
	v_exp_f32_e32 v79, v79
	v_pk_add_f32 v[92:93], v[92:93], v[204:205] op_sel_hi:[1,0] neg_lo:[0,1] neg_hi:[0,1]
	v_pk_add_f32 v[94:95], v[94:95], v[204:205] op_sel_hi:[1,0] neg_lo:[0,1] neg_hi:[0,1]
	ds_read_b128 v[160:163], v124 offset:4096
	ds_read_b128 v[148:151], v124 offset:4608
	v_mfma_f32_32x32x16_bf16 v[16:31], v[112:115], v[156:159], v[16:31]
	v_exp_f32_e32 v48, v48
	v_exp_f32_e32 v49, v49
	v_exp_f32_e32 v50, v50
	v_exp_f32_e32 v51, v51
	v_pk_add_f32 v[32:33], v[136:137], v[204:205] op_sel_hi:[1,0] neg_lo:[0,1] neg_hi:[0,1]
	v_pk_add_f32 v[34:35], v[138:139], v[204:205] op_sel_hi:[1,0] neg_lo:[0,1] neg_hi:[0,1]
	s_waitcnt lgkmcnt(6)
	ds_read_b128 v[156:159], v124 offset:6144
	ds_read_b128 v[136:139], v124 offset:6656
	v_mfma_f32_32x32x16_bf16 v[0:15], v[112:115], v[144:147], v[0:15]
	v_exp_f32_e32 v52, v52
	v_exp_f32_e32 v53, v53
	v_exp_f32_e32 v54, v54
	v_exp_f32_e32 v55, v55
	v_pk_add_f32 v[36:37], v[36:37], v[204:205] op_sel_hi:[1,0] neg_lo:[0,1] neg_hi:[0,1]
	v_pk_add_f32 v[38:39], v[38:39], v[204:205] op_sel_hi:[1,0] neg_lo:[0,1] neg_hi:[0,1]
	v_mfma_f32_32x32x16_bf16 v[16:31], v[104:107], v[140:143], v[16:31]
	v_exp_f32_e32 v56, v56
	v_exp_f32_e32 v57, v57
	v_exp_f32_e32 v58, v58
	v_exp_f32_e32 v59, v59
	v_pk_add_f32 v[40:41], v[40:41], v[204:205] op_sel_hi:[1,0] neg_lo:[0,1] neg_hi:[0,1]
	v_pk_add_f32 v[42:43], v[42:43], v[204:205] op_sel_hi:[1,0] neg_lo:[0,1] neg_hi:[0,1]
	v_mfma_f32_32x32x16_bf16 v[0:15], v[104:107], v[132:135], v[0:15]
	v_exp_f32_e32 v60, v60
	v_exp_f32_e32 v61, v61
	v_exp_f32_e32 v62, v62
	v_exp_f32_e32 v63, v63
	v_pk_add_f32 v[44:45], v[44:45], v[204:205] op_sel_hi:[1,0] neg_lo:[0,1] neg_hi:[0,1]
	v_pk_add_f32 v[46:47], v[46:47], v[204:205] op_sel_hi:[1,0] neg_lo:[0,1] neg_hi:[0,1]
	s_waitcnt vmcnt(2) lgkmcnt(0)
	s_barrier
	s_andn2_b64 vcc, exec, s[6:7]
	s_cbranch_vccnz .LBB0_151
	s_waitcnt lgkmcnt(0)
	ds_read_b128 v[132:135], v216 offset:49248
	ds_read_b128 v[140:143], v216 offset:49216
	ds_read_b128 v[144:147], v216 offset:49184
	ds_read_b128 v[172:175], v216 offset:49152
	s_waitcnt lgkmcnt(3)
	v_pk_mul_f32 v[30:31], v[30:31], v[134:135]
	s_waitcnt lgkmcnt(2)
	v_pk_mul_f32 v[26:27], v[26:27], v[142:143]
	s_waitcnt lgkmcnt(1)
	v_pk_mul_f32 v[22:23], v[22:23], v[146:147]
	s_waitcnt lgkmcnt(0)
	v_pk_mul_f32 v[18:19], v[18:19], v[174:175]
	v_pk_mul_f32 v[28:29], v[28:29], v[132:133]
	v_pk_mul_f32 v[24:25], v[24:25], v[140:141]
	v_pk_mul_f32 v[20:21], v[20:21], v[144:145]
	v_pk_mul_f32 v[16:17], v[16:17], v[172:173]
	v_pk_mul_f32 v[14:15], v[14:15], v[134:135]
	v_pk_mul_f32 v[10:11], v[10:11], v[142:143]
	v_pk_mul_f32 v[6:7], v[6:7], v[146:147]
	v_pk_mul_f32 v[2:3], v[2:3], v[174:175]
	v_pk_mul_f32 v[12:13], v[12:13], v[132:133]
	v_pk_mul_f32 v[8:9], v[8:9], v[140:141]
	v_pk_mul_f32 v[4:5], v[4:5], v[144:145]
	v_pk_mul_f32 v[0:1], v[0:1], v[172:173]
.LBB0_151:
	s_add_i32 s6, s28, 0x2000
	s_cmpk_lg_i32 s28, 0x4000
	s_cselect_b32 s22, s6, 0
	v_add_u32_e32 v182, s41, v221
	ds_read_b64_tr_b16 v[144:145], v182 offset:24576
	ds_read_b64_tr_b16 v[146:147], v182 offset:25088
	v_mfma_f32_32x32x16_bf16 v[80:95], v[168:171], v[116:119], v[80:95]
	v_add_f32_e32 v104, v64, v65
	v_add_f32_e32 v104, v66, v104
	v_add_f32_e32 v104, v67, v104
	v_add_f32_e32 v104, v68, v104
	v_add_f32_e32 v104, v69, v104
	v_cvt_pk_bf16_f32 v124, v64, v65
	v_cvt_pk_bf16_f32 v125, v66, v67
	ds_read_b64_tr_b16 v[140:141], v182 offset:28672
	ds_read_b64_tr_b16 v[142:143], v182 offset:29184
	v_mfma_f32_32x32x16_bf16 v[32:47], v[128:131], v[116:119], v[32:47]
	v_add_f32_e32 v64, v70, v104
	v_add_f32_e32 v64, v71, v64
	v_add_f32_e32 v64, v72, v64
	v_add_f32_e32 v64, v73, v64
	v_cvt_pk_bf16_f32 v126, v68, v69
	v_cvt_pk_bf16_f32 v127, v70, v71
	ds_read_b64_tr_b16 v[132:133], v182 offset:25600
	ds_read_b64_tr_b16 v[134:135], v182 offset:26112
	v_mfma_f32_32x32x16_bf16 v[80:95], v[164:167], v[108:111], v[80:95]
	v_add_f32_e32 v64, v74, v64
	v_add_f32_e32 v64, v75, v64
	v_add_f32_e32 v64, v76, v64
	v_add_f32_e32 v64, v77, v64
	v_cvt_pk_bf16_f32 v120, v72, v73
	v_cvt_pk_bf16_f32 v121, v74, v75
	ds_read_b64_tr_b16 v[128:129], v182 offset:29696
	ds_read_b64_tr_b16 v[130:131], v182 offset:30208
	v_mfma_f32_32x32x16_bf16 v[32:47], v[152:155], v[108:111], v[32:47]
	v_add_f32_e32 v64, v78, v64
	v_add_f32_e32 v64, v79, v64
	v_add_f32_e32 v64, v48, v64
	v_add_f32_e32 v64, v49, v64
	v_cvt_pk_bf16_f32 v122, v76, v77
	v_cvt_pk_bf16_f32 v123, v78, v79
	ds_read_b64_tr_b16 v[172:173], v182 offset:26624
	ds_read_b64_tr_b16 v[174:175], v182 offset:27136
	v_mfma_f32_32x32x16_bf16 v[80:95], v[160:163], v[100:103], v[80:95]
	v_add_f32_e32 v64, v50, v64
	v_add_f32_e32 v64, v51, v64
	v_add_f32_e32 v64, v52, v64
	v_add_f32_e32 v64, v53, v64
	v_cvt_pk_bf16_f32 v112, v48, v49
	v_cvt_pk_bf16_f32 v113, v50, v51
	ds_read_b64_tr_b16 v[168:169], v182 offset:30720
	ds_read_b64_tr_b16 v[170:171], v182 offset:31232
	v_mfma_f32_32x32x16_bf16 v[32:47], v[148:151], v[100:103], v[32:47]
	v_add_f32_e32 v48, v54, v64
	v_add_f32_e32 v48, v55, v48
	v_add_f32_e32 v48, v56, v48
	v_add_f32_e32 v48, v57, v48
	v_cvt_pk_bf16_f32 v114, v52, v53
	v_cvt_pk_bf16_f32 v115, v54, v55
	ds_read_b64_tr_b16 v[164:165], v182 offset:27648
	ds_read_b64_tr_b16 v[166:167], v182 offset:28160
	v_mfma_f32_32x32x16_bf16 v[80:95], v[156:159], v[96:99], v[80:95]
	v_add_f32_e32 v48, v58, v48
	v_add_f32_e32 v48, v59, v48
	v_add_f32_e32 v48, v60, v48
	v_add_f32_e32 v48, v61, v48
	v_cvt_pk_bf16_f32 v104, v56, v57
	v_cvt_pk_bf16_f32 v105, v58, v59
	ds_read_b64_tr_b16 v[160:161], v182 offset:31744
	ds_read_b64_tr_b16 v[162:163], v182 offset:32256
	v_mfma_f32_32x32x16_bf16 v[32:47], v[136:139], v[96:99], v[32:47]
	v_add_f32_e32 v48, v62, v48
	v_add_f32_e32 v48, v63, v48
	v_add_f32_e32 v48, 0, v48
	v_cvt_pk_bf16_f32 v106, v60, v61
	v_cvt_pk_bf16_f32 v107, v62, v63
	v_max_f32_e32 v49, v81, v81
	v_max_f32_e32 v50, v80, v80
	v_max_f32_e32 v49, v50, v49
	s_nop 3
	v_max3_f32 v50, v82, v83, v33
	v_max3_f32 v49, v49, v32, v34
	v_max3_f32 v49, v49, v35, v84
	v_max3_f32 v50, v50, v86, v87
	v_max3_f32 v49, v49, v85, v36
	v_max3_f32 v50, v50, v38, v39
	v_max3_f32 v49, v49, v37, v88
	v_max3_f32 v50, v50, v90, v91
	v_max3_f32 v49, v49, v89, v40
	v_max3_f32 v50, v50, v42, v43
	v_max3_f32 v49, v49, v41, v92
	v_max3_f32 v50, v50, v94, v95
	v_max3_f32 v49, v49, v93, v44
	v_max3_f32 v50, v50, v46, v47
	v_add_f32_e32 v222, v181, v48
	v_max3_f32 v48, v49, v45, v50
	v_mov_b32_e32 v49, v48
	s_nop 1
	v_permlane32_swap_b32_e32 v48, v49
	v_max_f32_e32 v49, v49, v49
	v_max_f32_e32 v48, v48, v48
	s_add_i32 s6, s28, s18
	s_mov_b32 m0, s6
	s_nop 0
	global_load_lds_dwordx4 v[178:179], off
	v_max_f32_e32 v48, v48, v49
	s_add_i32 s6, s22, s19
	s_mov_b32 m0, s6
	s_nop 0
	global_load_lds_dwordx4 v[176:177], off
	v_cmp_lt_f32_e32 vcc, s47, v48
	s_cmp_lg_u64 vcc, 0
	s_cselect_b64 s[6:7], -1, 0
	s_cbranch_vccnz .LBB0_159
.LBB0_152:
	ds_read_b128 v[48:51], v180 offset:256
	ds_read_b128 v[68:71], v180 offset:288
	ds_read_b128 v[136:139], v180 offset:384
	ds_read_b128 v[52:55], v180 offset:416
	ds_read_b128 v[72:75], v180 offset:320
	ds_read_b128 v[76:79], v180 offset:352
	ds_read_b128 v[56:59], v180 offset:448
	ds_read_b128 v[60:63], v180 offset:480
	s_waitcnt lgkmcnt(14)
	v_mfma_f32_32x32x16_bf16 v[16:31], v[124:127], v[144:147], v[16:31]
	v_exp_f32_e32 v80, v80
	v_exp_f32_e32 v81, v81
	v_exp_f32_e32 v82, v82
	v_exp_f32_e32 v83, v83
	s_waitcnt lgkmcnt(7)
	v_pk_add_f32 v[64:65], v[48:49], v[204:205] op_sel_hi:[1,0] neg_lo:[0,1] neg_hi:[0,1]
	v_pk_add_f32 v[66:67], v[50:51], v[204:205] op_sel_hi:[1,0] neg_lo:[0,1] neg_hi:[0,1]
	s_waitcnt lgkmcnt(2)
	v_mfma_f32_32x32x16_bf16 v[0:15], v[124:127], v[140:143], v[0:15]
	v_exp_f32_e32 v84, v84
	v_exp_f32_e32 v85, v85
	v_exp_f32_e32 v86, v86
	v_exp_f32_e32 v87, v87
	v_pk_add_f32 v[68:69], v[68:69], v[204:205] op_sel_hi:[1,0] neg_lo:[0,1] neg_hi:[0,1]
	v_pk_add_f32 v[70:71], v[70:71], v[204:205] op_sel_hi:[1,0] neg_lo:[0,1] neg_hi:[0,1]
	v_add_u32_e32 v124, s22, v220
	ds_read_b128 v[156:159], v124
	ds_read_b128 v[152:155], v124 offset:512
	v_mfma_f32_32x32x16_bf16 v[16:31], v[120:123], v[132:135], v[16:31]
	v_exp_f32_e32 v88, v88
	v_exp_f32_e32 v89, v89
	v_exp_f32_e32 v90, v90
	v_exp_f32_e32 v91, v91
	v_pk_add_f32 v[72:73], v[72:73], v[204:205] op_sel_hi:[1,0] neg_lo:[0,1] neg_hi:[0,1]
	v_pk_add_f32 v[74:75], v[74:75], v[204:205] op_sel_hi:[1,0] neg_lo:[0,1] neg_hi:[0,1]
	ds_read_b128 v[148:151], v124 offset:2048
	ds_read_b128 v[144:147], v124 offset:2560
	v_mfma_f32_32x32x16_bf16 v[0:15], v[120:123], v[128:131], v[0:15]
	v_exp_f32_e32 v92, v92
	v_exp_f32_e32 v93, v93
	v_exp_f32_e32 v94, v94
	v_exp_f32_e32 v95, v95
	v_pk_add_f32 v[76:77], v[76:77], v[204:205] op_sel_hi:[1,0] neg_lo:[0,1] neg_hi:[0,1]
	v_pk_add_f32 v[78:79], v[78:79], v[204:205] op_sel_hi:[1,0] neg_lo:[0,1] neg_hi:[0,1]
	ds_read_b128 v[140:143], v124 offset:4096
	ds_read_b128 v[132:135], v124 offset:4608
	v_mfma_f32_32x32x16_bf16 v[16:31], v[112:115], v[172:175], v[16:31]
	v_exp_f32_e32 v32, v32
	v_exp_f32_e32 v33, v33
	v_exp_f32_e32 v34, v34
	v_exp_f32_e32 v35, v35
	v_pk_add_f32 v[48:49], v[136:137], v[204:205] op_sel_hi:[1,0] neg_lo:[0,1] neg_hi:[0,1]
	v_pk_add_f32 v[50:51], v[138:139], v[204:205] op_sel_hi:[1,0] neg_lo:[0,1] neg_hi:[0,1]
	s_waitcnt lgkmcnt(6)
	ds_read_b128 v[136:139], v124 offset:6144
	ds_read_b128 v[128:131], v124 offset:6656
	v_mfma_f32_32x32x16_bf16 v[0:15], v[112:115], v[168:171], v[0:15]
	v_exp_f32_e32 v36, v36
	v_exp_f32_e32 v37, v37
	v_exp_f32_e32 v38, v38
	v_exp_f32_e32 v39, v39
	v_pk_add_f32 v[52:53], v[52:53], v[204:205] op_sel_hi:[1,0] neg_lo:[0,1] neg_hi:[0,1]
	v_pk_add_f32 v[54:55], v[54:55], v[204:205] op_sel_hi:[1,0] neg_lo:[0,1] neg_hi:[0,1]
	v_mfma_f32_32x32x16_bf16 v[16:31], v[104:107], v[164:167], v[16:31]
	v_exp_f32_e32 v40, v40
	v_exp_f32_e32 v41, v41
	v_exp_f32_e32 v42, v42
	v_exp_f32_e32 v43, v43
	v_pk_add_f32 v[56:57], v[56:57], v[204:205] op_sel_hi:[1,0] neg_lo:[0,1] neg_hi:[0,1]
	v_pk_add_f32 v[58:59], v[58:59], v[204:205] op_sel_hi:[1,0] neg_lo:[0,1] neg_hi:[0,1]
	v_mfma_f32_32x32x16_bf16 v[0:15], v[104:107], v[160:163], v[0:15]
	v_exp_f32_e32 v44, v44
	v_exp_f32_e32 v45, v45
	v_exp_f32_e32 v46, v46
	v_exp_f32_e32 v47, v47
	v_pk_add_f32 v[60:61], v[60:61], v[204:205] op_sel_hi:[1,0] neg_lo:[0,1] neg_hi:[0,1]
	v_pk_add_f32 v[62:63], v[62:63], v[204:205] op_sel_hi:[1,0] neg_lo:[0,1] neg_hi:[0,1]
	s_waitcnt vmcnt(2) lgkmcnt(0)
	s_barrier
	s_andn2_b64 vcc, exec, s[6:7]
	s_cbranch_vccnz .LBB0_154
	s_waitcnt lgkmcnt(0)
	ds_read_b128 v[160:163], v216 offset:49248
	ds_read_b128 v[164:167], v216 offset:49216
	ds_read_b128 v[168:171], v216 offset:49184
	ds_read_b128 v[172:175], v216 offset:49152
	s_waitcnt lgkmcnt(3)
	v_pk_mul_f32 v[30:31], v[30:31], v[162:163]
	s_waitcnt lgkmcnt(2)
	v_pk_mul_f32 v[26:27], v[26:27], v[166:167]
	s_waitcnt lgkmcnt(1)
	v_pk_mul_f32 v[22:23], v[22:23], v[170:171]
	s_waitcnt lgkmcnt(0)
	v_pk_mul_f32 v[18:19], v[18:19], v[174:175]
	v_pk_mul_f32 v[28:29], v[28:29], v[160:161]
	v_pk_mul_f32 v[24:25], v[24:25], v[164:165]
	v_pk_mul_f32 v[20:21], v[20:21], v[168:169]
	v_pk_mul_f32 v[16:17], v[16:17], v[172:173]
	v_pk_mul_f32 v[14:15], v[14:15], v[162:163]
	v_pk_mul_f32 v[10:11], v[10:11], v[166:167]
	v_pk_mul_f32 v[6:7], v[6:7], v[170:171]
	v_pk_mul_f32 v[2:3], v[2:3], v[174:175]
	v_pk_mul_f32 v[12:13], v[12:13], v[160:161]
	v_pk_mul_f32 v[8:9], v[8:9], v[164:165]
	v_pk_mul_f32 v[4:5], v[4:5], v[168:169]
	v_pk_mul_f32 v[0:1], v[0:1], v[172:173]

.LBB0_167:
	v_add_u32_e32 v164, s24, v221
	ds_read_b64_tr_b16 v[160:161], v164 offset:24576
	ds_read_b64_tr_b16 v[162:163], v164 offset:25088
	v_mfma_f32_32x32x16_bf16 v[64:79], v[156:159], v[116:119], v[64:79]
	v_add_f32_e32 v104, v80, v81
	v_add_f32_e32 v104, v82, v104
	v_add_f32_e32 v104, v83, v104
	v_add_f32_e32 v104, v84, v104
	v_add_f32_e32 v104, v85, v104
	v_cvt_pk_bf16_f32 v124, v80, v81
	v_cvt_pk_bf16_f32 v125, v82, v83
	ds_read_b64_tr_b16 v[156:157], v164 offset:28672
	ds_read_b64_tr_b16 v[158:159], v164 offset:29184
	v_mfma_f32_32x32x16_bf16 v[48:63], v[152:155], v[116:119], v[48:63]
	v_add_f32_e32 v104, v86, v104
	v_add_f32_e32 v104, v87, v104
	v_add_f32_e32 v104, v88, v104
	v_add_f32_e32 v104, v89, v104
	v_cvt_pk_bf16_f32 v126, v84, v85
	v_cvt_pk_bf16_f32 v127, v86, v87
	ds_read_b64_tr_b16 v[152:153], v164 offset:25600
	ds_read_b64_tr_b16 v[154:155], v164 offset:26112
	v_mfma_f32_32x32x16_bf16 v[64:79], v[148:151], v[108:111], v[64:79]
	v_add_f32_e32 v104, v90, v104
	v_add_f32_e32 v104, v91, v104
	v_add_f32_e32 v104, v92, v104
	v_add_f32_e32 v104, v93, v104
	v_cvt_pk_bf16_f32 v120, v88, v89
	v_cvt_pk_bf16_f32 v121, v90, v91
	ds_read_b64_tr_b16 v[148:149], v164 offset:29696
	ds_read_b64_tr_b16 v[150:151], v164 offset:30208
	v_mfma_f32_32x32x16_bf16 v[48:63], v[144:147], v[108:111], v[48:63]
	v_add_f32_e32 v104, v94, v104
	v_add_f32_e32 v104, v95, v104
	v_add_f32_e32 v104, v32, v104
	v_add_f32_e32 v104, v33, v104
	v_cvt_pk_bf16_f32 v122, v92, v93
	v_cvt_pk_bf16_f32 v123, v94, v95
	ds_read_b64_tr_b16 v[144:145], v164 offset:26624
	ds_read_b64_tr_b16 v[146:147], v164 offset:27136
	v_mfma_f32_32x32x16_bf16 v[64:79], v[140:143], v[100:103], v[64:79]
	v_add_f32_e32 v104, v34, v104
	v_add_f32_e32 v104, v35, v104
	v_add_f32_e32 v104, v36, v104
	v_add_f32_e32 v104, v37, v104
	v_cvt_pk_bf16_f32 v112, v32, v33
	v_cvt_pk_bf16_f32 v113, v34, v35
	ds_read_b64_tr_b16 v[116:117], v164 offset:30720
	ds_read_b64_tr_b16 v[118:119], v164 offset:31232
	v_mfma_f32_32x32x16_bf16 v[48:63], v[132:135], v[100:103], v[48:63]
	v_add_f32_e32 v100, v38, v104
	v_add_f32_e32 v100, v39, v100
	v_add_f32_e32 v100, v40, v100
	v_add_f32_e32 v100, v41, v100
	v_cvt_pk_bf16_f32 v114, v36, v37
	v_cvt_pk_bf16_f32 v115, v38, v39
	ds_read_b64_tr_b16 v[108:109], v164 offset:27648
	ds_read_b64_tr_b16 v[110:111], v164 offset:28160
	v_mfma_f32_32x32x16_bf16 v[64:79], v[136:139], v[96:99], v[64:79]
	v_add_f32_e32 v100, v42, v100
	v_add_f32_e32 v100, v43, v100
	v_add_f32_e32 v100, v44, v100
	v_add_f32_e32 v132, v45, v100
	v_cvt_pk_bf16_f32 v104, v40, v41
	v_cvt_pk_bf16_f32 v105, v42, v43
	ds_read_b64_tr_b16 v[100:101], v164 offset:31744
	ds_read_b64_tr_b16 v[102:103], v164 offset:32256
	v_mfma_f32_32x32x16_bf16 v[48:63], v[128:131], v[96:99], v[48:63]
	v_add_f32_e32 v96, v46, v132
	v_add_f32_e32 v96, v47, v96
	v_add_f32_e32 v96, 0, v96
	v_cvt_pk_bf16_f32 v106, v44, v45
	v_cvt_pk_bf16_f32 v107, v46, v47
	v_or_b32_e32 v98, 0xe0, v218
	v_or_b32_e32 v97, 0xc0, v218
	v_cmp_le_i32_e32 vcc, v98, v219
	v_add_f32_e32 v96, v222, v96
	s_nop 2
	v_cndmask_b32_e32 v48, v238, v48, vcc
	v_cmp_lt_i32_e32 vcc, v97, v219
	s_nop 1
	v_cndmask_b32_e32 v65, v238, v65, vcc
	v_cmp_le_i32_e32 vcc, v97, v219
	v_or_b32_e32 v97, 0xe1, v218
	s_nop 0
	v_cndmask_b32_e32 v64, v238, v64, vcc
	v_cmp_le_i32_e32 vcc, v97, v219
	v_or_b32_e32 v97, 0xc2, v218
	v_max_f32_e32 v98, v64, v64
	v_cndmask_b32_e32 v49, v238, v49, vcc
	v_cmp_le_i32_e32 vcc, v97, v219
	v_or_b32_e32 v97, 0xe2, v218
	s_nop 0
	v_cndmask_b32_e32 v66, v238, v66, vcc
	v_cmp_le_i32_e32 vcc, v97, v219
	v_or_b32_e32 v97, 0xc3, v218
	s_nop 0
	v_cndmask_b32_e32 v50, v238, v50, vcc
	v_cmp_le_i32_e32 vcc, v97, v219
	v_or_b32_e32 v97, 0xe3, v218
	s_nop 0
	v_cndmask_b32_e32 v67, v238, v67, vcc
	v_cmp_le_i32_e32 vcc, v97, v219
	v_or_b32_e32 v97, 0xc8, v218
	s_nop 0
	v_cndmask_b32_e32 v51, v238, v51, vcc
	v_cmp_le_i32_e32 vcc, v97, v219
	v_or_b32_e32 v97, 0xe8, v218
	s_nop 0
	v_cndmask_b32_e32 v68, v238, v68, vcc
	v_cmp_le_i32_e32 vcc, v97, v219
	v_or_b32_e32 v97, 0xc9, v218
	s_nop 0
	v_cndmask_b32_e32 v52, v238, v52, vcc
	v_cmp_le_i32_e32 vcc, v97, v219
	v_or_b32_e32 v97, 0xe9, v218
	s_nop 0
	v_cndmask_b32_e32 v69, v238, v69, vcc
	v_cmp_le_i32_e32 vcc, v97, v219
	v_or_b32_e32 v97, 0xca, v218
	s_nop 0
	v_cndmask_b32_e32 v53, v238, v53, vcc
	v_cmp_le_i32_e32 vcc, v97, v219
	v_or_b32_e32 v97, 0xea, v218
	s_nop 0
	v_cndmask_b32_e32 v70, v238, v70, vcc
	v_cmp_le_i32_e32 vcc, v97, v219
	v_or_b32_e32 v97, 0xcb, v218
	s_nop 0
	v_cndmask_b32_e32 v54, v238, v54, vcc
	v_cmp_le_i32_e32 vcc, v97, v219
	v_or_b32_e32 v97, 0xeb, v218
	s_nop 0
	v_cndmask_b32_e32 v71, v238, v71, vcc
	v_cmp_le_i32_e32 vcc, v97, v219
	v_or_b32_e32 v97, 0xd0, v218
	s_nop 0
	v_cndmask_b32_e32 v55, v238, v55, vcc
	v_cmp_le_i32_e32 vcc, v97, v219
	v_or_b32_e32 v97, 0xf0, v218
	s_nop 0
	v_cndmask_b32_e32 v72, v238, v72, vcc
	v_cmp_le_i32_e32 vcc, v97, v219
	v_or_b32_e32 v97, 0xd1, v218
	s_nop 0
	v_cndmask_b32_e32 v56, v238, v56, vcc
	v_cmp_le_i32_e32 vcc, v97, v219
	v_or_b32_e32 v97, 0xf1, v218
	s_nop 0
	v_cndmask_b32_e32 v73, v238, v73, vcc
	v_cmp_le_i32_e32 vcc, v97, v219
	v_or_b32_e32 v97, 0xd2, v218
	s_nop 0
	v_cndmask_b32_e32 v57, v238, v57, vcc
	v_cmp_le_i32_e32 vcc, v97, v219
	v_or_b32_e32 v97, 0xf2, v218
	s_nop 0
	v_cndmask_b32_e32 v74, v238, v74, vcc
	v_cmp_le_i32_e32 vcc, v97, v219
	v_or_b32_e32 v97, 0xd3, v218
	s_nop 0
	v_cndmask_b32_e32 v58, v238, v58, vcc
	v_cmp_le_i32_e32 vcc, v97, v219
	v_or_b32_e32 v97, 0xf3, v218
	s_nop 0
	v_cndmask_b32_e32 v75, v238, v75, vcc
	v_cmp_le_i32_e32 vcc, v97, v219
	v_or_b32_e32 v97, 0xd8, v218
	s_nop 0
	v_cndmask_b32_e32 v59, v238, v59, vcc
	v_cmp_le_i32_e32 vcc, v97, v219
	v_or_b32_e32 v97, 0xf8, v218
	s_nop 0
	v_cndmask_b32_e32 v76, v238, v76, vcc
	v_cmp_le_i32_e32 vcc, v97, v219
	v_or_b32_e32 v97, 0xd9, v218
	s_nop 0
	v_cndmask_b32_e32 v60, v238, v60, vcc
	v_cmp_le_i32_e32 vcc, v97, v219
	v_or_b32_e32 v97, 0xf9, v218
	s_nop 0
	v_cndmask_b32_e32 v77, v238, v77, vcc
	v_cmp_le_i32_e32 vcc, v97, v219
	v_or_b32_e32 v97, 0xda, v218
	s_nop 0
	v_cndmask_b32_e32 v61, v238, v61, vcc
	v_cmp_le_i32_e32 vcc, v97, v219
	v_or_b32_e32 v97, 0xfa, v218
	s_nop 0
	v_cndmask_b32_e32 v78, v238, v78, vcc
	v_cmp_le_i32_e32 vcc, v97, v219
	v_or_b32_e32 v97, 0xdb, v218
	s_nop 0
	v_cndmask_b32_e32 v62, v238, v62, vcc
	v_cmp_le_i32_e32 vcc, v97, v219
	v_or_b32_e32 v97, 0xfb, v218
	s_nop 0
	v_cndmask_b32_e32 v79, v238, v79, vcc
	v_cmp_le_i32_e32 vcc, v97, v219
	v_max_f32_e32 v97, v65, v65
	v_max_f32_e32 v97, v98, v97
	v_max3_f32 v98, v66, v67, v49
	v_max3_f32 v97, v97, v48, v50
	v_max3_f32 v97, v97, v51, v68
	v_max3_f32 v98, v98, v70, v71
	v_max3_f32 v97, v97, v69, v52
	v_max3_f32 v98, v98, v54, v55
	v_max3_f32 v97, v97, v53, v72
	v_max3_f32 v98, v98, v74, v75
	v_max3_f32 v97, v97, v73, v56
	v_max3_f32 v98, v98, v58, v59
	v_cndmask_b32_e32 v63, v238, v63, vcc
	v_max3_f32 v97, v97, v57, v76
	v_max3_f32 v98, v98, v78, v79
	v_max3_f32 v97, v97, v77, v60
	v_max3_f32 v98, v98, v62, v63
	v_max3_f32 v97, v97, v61, v98
	v_mov_b32_e32 v98, v97
	s_nop 1
	v_permlane32_swap_b32_e32 v97, v98
	v_max_f32_e32 v98, v98, v98
	v_max_f32_e32 v97, v97, v97
	v_max_f32_e32 v97, v97, v98
	v_cmp_lt_f32_e32 vcc, s47, v97
	s_cmp_lg_u64 vcc, 0
	s_cselect_b64 s[4:5], -1, 0
	s_cbranch_vccnz .LBB0_224
.LBB0_168:
	s_waitcnt lgkmcnt(14)
	v_mfma_f32_32x32x16_bf16 v[16:31], v[124:127], v[160:163], v[16:31]
	v_exp_f32_e32 v64, v64
	v_exp_f32_e32 v65, v65
	v_exp_f32_e32 v66, v66
	v_exp_f32_e32 v67, v67
	v_sub_f32_e32 v81, v81, v204
	v_sub_f32_e32 v80, v80, v204
	v_pk_add_f32 v[82:83], v[82:83], v[204:205] op_sel_hi:[1,0] neg_lo:[0,1] neg_hi:[0,1]
	s_waitcnt lgkmcnt(12)
	v_mfma_f32_32x32x16_bf16 v[0:15], v[124:127], v[156:159], v[0:15]
	v_exp_f32_e32 v68, v68
	v_exp_f32_e32 v69, v69
	v_exp_f32_e32 v70, v70
	v_exp_f32_e32 v71, v71
	v_pk_add_f32 v[84:85], v[84:85], v[204:205] op_sel_hi:[1,0] neg_lo:[0,1] neg_hi:[0,1]
	v_pk_add_f32 v[86:87], v[86:87], v[204:205] op_sel_hi:[1,0] neg_lo:[0,1] neg_hi:[0,1]
	s_waitcnt lgkmcnt(10)
	v_mfma_f32_32x32x16_bf16 v[16:31], v[120:123], v[152:155], v[16:31]
	v_exp_f32_e32 v72, v72
	v_exp_f32_e32 v73, v73
	v_exp_f32_e32 v74, v74
	v_exp_f32_e32 v75, v75
	v_pk_add_f32 v[88:89], v[88:89], v[204:205] op_sel_hi:[1,0] neg_lo:[0,1] neg_hi:[0,1]
	v_pk_add_f32 v[90:91], v[90:91], v[204:205] op_sel_hi:[1,0] neg_lo:[0,1] neg_hi:[0,1]
	s_waitcnt lgkmcnt(8)
	v_mfma_f32_32x32x16_bf16 v[0:15], v[120:123], v[148:151], v[0:15]
	v_exp_f32_e32 v76, v76
	v_exp_f32_e32 v77, v77
	v_exp_f32_e32 v78, v78
	v_exp_f32_e32 v79, v79
	v_pk_add_f32 v[92:93], v[92:93], v[204:205] op_sel_hi:[1,0] neg_lo:[0,1] neg_hi:[0,1]
	v_pk_add_f32 v[94:95], v[94:95], v[204:205] op_sel_hi:[1,0] neg_lo:[0,1] neg_hi:[0,1]
	s_waitcnt lgkmcnt(6)
	v_mfma_f32_32x32x16_bf16 v[16:31], v[112:115], v[144:147], v[16:31]
	v_exp_f32_e32 v48, v48
	v_exp_f32_e32 v49, v49
	v_exp_f32_e32 v50, v50
	v_exp_f32_e32 v51, v51
	v_sub_f32_e32 v33, v33, v204
	v_sub_f32_e32 v32, v32, v204
	v_pk_add_f32 v[34:35], v[34:35], v[204:205] op_sel_hi:[1,0] neg_lo:[0,1] neg_hi:[0,1]
	s_waitcnt lgkmcnt(4)
	v_mfma_f32_32x32x16_bf16 v[0:15], v[112:115], v[116:119], v[0:15]
	v_exp_f32_e32 v52, v52
	v_exp_f32_e32 v53, v53
	v_exp_f32_e32 v54, v54
	v_exp_f32_e32 v55, v55
	v_pk_add_f32 v[36:37], v[36:37], v[204:205] op_sel_hi:[1,0] neg_lo:[0,1] neg_hi:[0,1]
	v_pk_add_f32 v[38:39], v[38:39], v[204:205] op_sel_hi:[1,0] neg_lo:[0,1] neg_hi:[0,1]
	s_waitcnt lgkmcnt(2)
	v_mfma_f32_32x32x16_bf16 v[16:31], v[104:107], v[108:111], v[16:31]
	v_exp_f32_e32 v56, v56
	v_exp_f32_e32 v57, v57
	v_exp_f32_e32 v58, v58
	v_exp_f32_e32 v59, v59
	v_pk_add_f32 v[40:41], v[40:41], v[204:205] op_sel_hi:[1,0] neg_lo:[0,1] neg_hi:[0,1]
	v_pk_add_f32 v[42:43], v[42:43], v[204:205] op_sel_hi:[1,0] neg_lo:[0,1] neg_hi:[0,1]
	s_waitcnt lgkmcnt(0)
	v_mfma_f32_32x32x16_bf16 v[0:15], v[104:107], v[100:103], v[0:15]
	v_exp_f32_e32 v60, v60
	v_exp_f32_e32 v61, v61
	v_exp_f32_e32 v62, v62
	v_exp_f32_e32 v63, v63
	v_pk_add_f32 v[44:45], v[44:45], v[204:205] op_sel_hi:[1,0] neg_lo:[0,1] neg_hi:[0,1]
	v_pk_add_f32 v[46:47], v[46:47], v[204:205] op_sel_hi:[1,0] neg_lo:[0,1] neg_hi:[0,1]
	s_andn2_b64 vcc, exec, s[4:5]
	s_cbranch_vccnz .LBB0_170
	s_waitcnt lgkmcnt(0)
	ds_read_b128 v[32:35], v216 offset:49248
	ds_read_b128 v[36:39], v216 offset:49216
	ds_read_b128 v[40:43], v216 offset:49184
	ds_read_b128 v[44:47], v216 offset:49152
	s_waitcnt lgkmcnt(3)
	v_pk_mul_f32 v[30:31], v[30:31], v[34:35]
	s_waitcnt lgkmcnt(2)
	v_pk_mul_f32 v[26:27], v[26:27], v[38:39]
	s_waitcnt lgkmcnt(1)
	v_pk_mul_f32 v[22:23], v[22:23], v[42:43]
	s_waitcnt lgkmcnt(0)
	v_pk_mul_f32 v[18:19], v[18:19], v[46:47]
	v_pk_mul_f32 v[28:29], v[28:29], v[32:33]
	v_pk_mul_f32 v[24:25], v[24:25], v[36:37]
	v_pk_mul_f32 v[20:21], v[20:21], v[40:41]
	v_pk_mul_f32 v[16:17], v[16:17], v[44:45]
	v_pk_mul_f32 v[14:15], v[14:15], v[34:35]
	v_pk_mul_f32 v[10:11], v[10:11], v[38:39]
	v_pk_mul_f32 v[6:7], v[6:7], v[42:43]
	v_pk_mul_f32 v[2:3], v[2:3], v[46:47]
	v_pk_mul_f32 v[12:13], v[12:13], v[32:33]
	v_pk_mul_f32 v[8:9], v[8:9], v[36:37]
	v_pk_mul_f32 v[4:5], v[4:5], v[40:41]
	v_pk_mul_f32 v[0:1], v[0:1], v[44:45]

.LBB0_174:
	v_add_u32_e32 v162, s28, v221
	ds_read_b64_tr_b16 v[184:185], v162 offset:24576
	ds_read_b64_tr_b16 v[186:187], v162 offset:25088
	v_mfma_f32_32x32x16_bf16 v[64:79], v[156:159], v[116:119], v[64:79]
	v_add_f32_e32 v104, v80, v81
	v_add_f32_e32 v104, v82, v104
	v_add_f32_e32 v104, v83, v104
	v_add_f32_e32 v104, v84, v104
	v_add_f32_e32 v104, v85, v104
	v_cvt_pk_bf16_f32 v124, v80, v81
	v_cvt_pk_bf16_f32 v125, v82, v83
	ds_read_b64_tr_b16 v[156:157], v162 offset:28672
	ds_read_b64_tr_b16 v[158:159], v162 offset:29184
	v_mfma_f32_32x32x16_bf16 v[48:63], v[152:155], v[116:119], v[48:63]
	v_add_f32_e32 v80, v86, v104
	v_add_f32_e32 v80, v87, v80
	v_add_f32_e32 v80, v88, v80
	v_add_f32_e32 v80, v89, v80
	v_cvt_pk_bf16_f32 v126, v84, v85
	v_cvt_pk_bf16_f32 v127, v86, v87
	ds_read_b64_tr_b16 v[176:177], v162 offset:25600
	ds_read_b64_tr_b16 v[178:179], v162 offset:26112
	v_mfma_f32_32x32x16_bf16 v[64:79], v[148:151], v[108:111], v[64:79]
	v_add_f32_e32 v80, v90, v80
	v_add_f32_e32 v80, v91, v80
	v_add_f32_e32 v80, v92, v80
	v_add_f32_e32 v80, v93, v80
	v_cvt_pk_bf16_f32 v120, v88, v89
	v_cvt_pk_bf16_f32 v121, v90, v91
	ds_read_b64_tr_b16 v[172:173], v162 offset:29696
	ds_read_b64_tr_b16 v[174:175], v162 offset:30208
	v_mfma_f32_32x32x16_bf16 v[48:63], v[144:147], v[108:111], v[48:63]
	v_add_f32_e32 v80, v94, v80
	v_add_f32_e32 v80, v95, v80
	v_add_f32_e32 v80, v32, v80
	v_add_f32_e32 v80, v33, v80
	v_cvt_pk_bf16_f32 v122, v92, v93
	v_cvt_pk_bf16_f32 v123, v94, v95
	ds_read_b64_tr_b16 v[180:181], v162 offset:26624
	ds_read_b64_tr_b16 v[182:183], v162 offset:27136
	v_mfma_f32_32x32x16_bf16 v[64:79], v[140:143], v[100:103], v[64:79]
	v_add_f32_e32 v80, v34, v80
	v_add_f32_e32 v80, v35, v80
	v_add_f32_e32 v80, v36, v80
	v_add_f32_e32 v80, v37, v80
	v_cvt_pk_bf16_f32 v112, v32, v33
	v_cvt_pk_bf16_f32 v113, v34, v35
	ds_read_b64_tr_b16 v[168:169], v162 offset:30720
	ds_read_b64_tr_b16 v[170:171], v162 offset:31232
	v_mfma_f32_32x32x16_bf16 v[48:63], v[132:135], v[100:103], v[48:63]
	v_add_f32_e32 v32, v38, v80
	v_add_f32_e32 v32, v39, v32
	v_add_f32_e32 v32, v40, v32
	v_add_f32_e32 v32, v41, v32
	v_cvt_pk_bf16_f32 v114, v36, v37
	v_cvt_pk_bf16_f32 v115, v38, v39
	ds_read_b64_tr_b16 v[164:165], v162 offset:27648
	ds_read_b64_tr_b16 v[166:167], v162 offset:28160
	v_mfma_f32_32x32x16_bf16 v[64:79], v[136:139], v[96:99], v[64:79]
	v_add_f32_e32 v32, v42, v32
	v_add_f32_e32 v32, v43, v32
	v_add_f32_e32 v32, v44, v32
	v_add_f32_e32 v32, v45, v32
	v_cvt_pk_bf16_f32 v104, v40, v41
	v_cvt_pk_bf16_f32 v105, v42, v43
	ds_read_b64_tr_b16 v[160:161], v162 offset:31744
	ds_read_b64_tr_b16 v[162:163], v162 offset:32256
	v_mfma_f32_32x32x16_bf16 v[48:63], v[128:131], v[96:99], v[48:63]
	v_add_f32_e32 v32, v46, v32
	v_add_f32_e32 v32, v47, v32
	v_add_f32_e32 v32, 0, v32
	v_cvt_pk_bf16_f32 v106, v44, v45
	v_cvt_pk_bf16_f32 v107, v46, v47
	s_add_i32 s78, s4, 1
	s_cmp_ge_i32 s78, s20
	s_cselect_b64 s[40:41], -1, 0
	s_and_b64 vcc, exec, s[40:41]
	s_cbranch_vccnz .LBB0_176
	s_lshl_b64 s[16:17], s[78:79], 17
	s_add_i32 s5, s22, s18
	v_lshl_add_u64 v[34:35], v[206:207], 0, s[16:17]
	s_mov_b32 m0, s5
	s_nop 0
	global_load_lds_dwordx4 v[34:35], off
.LBB0_176:
	s_add_i32 s78, s4, -1
	s_lshl_b64 s[16:17], s[78:79], 17
	s_add_i32 s28, s26, s4
	v_lshl_add_u64 v[34:35], v[208:209], 0, s[16:17]
	s_add_i32 s5, s24, s19
	s_add_i32 s16, s28, 2
	s_cmp_lt_i32 s16, 0
	s_mov_b32 m0, s5
	s_nop 0
	global_load_lds_dwordx4 v[34:35], off
	s_cbranch_scc1 .LBB0_178
	v_add_u32_e32 v33, 32, v223
	v_cmp_le_i32_e32 vcc, v33, v219
	v_add_u32_e32 v33, 33, v223
	s_nop 0
	v_cndmask_b32_e32 v48, v238, v48, vcc
	v_cmp_lt_i32_e32 vcc, v223, v219
	s_nop 1
	v_cndmask_b32_e32 v65, v238, v65, vcc
	v_cmp_le_i32_e32 vcc, v223, v219
	s_nop 1
	v_cndmask_b32_e32 v64, v238, v64, vcc
	v_cmp_le_i32_e32 vcc, v33, v219
	v_add_u32_e32 v33, 2, v223
	s_nop 0
	v_cndmask_b32_e32 v49, v238, v49, vcc
	v_cmp_le_i32_e32 vcc, v33, v219
	v_add_u32_e32 v33, 34, v223
	s_nop 0
	v_cndmask_b32_e32 v66, v238, v66, vcc
	v_cmp_le_i32_e32 vcc, v33, v219
	v_add_u32_e32 v33, 3, v223
	s_nop 0
	v_cndmask_b32_e32 v50, v238, v50, vcc
	v_cmp_le_i32_e32 vcc, v33, v219
	v_add_u32_e32 v33, 35, v223
	s_nop 0
	v_cndmask_b32_e32 v67, v238, v67, vcc
	v_cmp_le_i32_e32 vcc, v33, v219
	v_add_u32_e32 v33, 8, v223
	s_nop 0
	v_cndmask_b32_e32 v51, v238, v51, vcc
	v_cmp_le_i32_e32 vcc, v33, v219
	v_add_u32_e32 v33, 40, v223
	s_nop 0
	v_cndmask_b32_e32 v68, v238, v68, vcc
	v_cmp_le_i32_e32 vcc, v33, v219
	v_add_u32_e32 v33, 9, v223
	s_nop 0
	v_cndmask_b32_e32 v52, v238, v52, vcc
	v_cmp_le_i32_e32 vcc, v33, v219
	v_add_u32_e32 v33, 41, v223
	s_nop 0
	v_cndmask_b32_e32 v69, v238, v69, vcc
	v_cmp_le_i32_e32 vcc, v33, v219
	v_add_u32_e32 v33, 10, v223
	s_nop 0
	v_cndmask_b32_e32 v53, v238, v53, vcc
	v_cmp_le_i32_e32 vcc, v33, v219
	v_add_u32_e32 v33, 42, v223
	s_nop 0
	v_cndmask_b32_e32 v70, v238, v70, vcc
	v_cmp_le_i32_e32 vcc, v33, v219
	v_add_u32_e32 v33, 11, v223
	s_nop 0
	v_cndmask_b32_e32 v54, v238, v54, vcc
	v_cmp_le_i32_e32 vcc, v33, v219
	v_add_u32_e32 v33, 43, v223
	s_nop 0
	v_cndmask_b32_e32 v71, v238, v71, vcc
	v_cmp_le_i32_e32 vcc, v33, v219
	v_add_u32_e32 v33, 16, v223
	s_nop 0
	v_cndmask_b32_e32 v55, v238, v55, vcc
	v_cmp_le_i32_e32 vcc, v33, v219
	v_add_u32_e32 v33, 48, v223
	s_nop 0
	v_cndmask_b32_e32 v72, v238, v72, vcc
	v_cmp_le_i32_e32 vcc, v33, v219
	v_add_u32_e32 v33, 17, v223
	s_nop 0
	v_cndmask_b32_e32 v56, v238, v56, vcc
	v_cmp_le_i32_e32 vcc, v33, v219
	v_add_u32_e32 v33, 49, v223
	s_nop 0
	v_cndmask_b32_e32 v73, v238, v73, vcc
	v_cmp_le_i32_e32 vcc, v33, v219
	v_add_u32_e32 v33, 18, v223
	s_nop 0
	v_cndmask_b32_e32 v57, v238, v57, vcc
	v_cmp_le_i32_e32 vcc, v33, v219
	v_add_u32_e32 v33, 50, v223
	s_nop 0
	v_cndmask_b32_e32 v74, v238, v74, vcc
	v_cmp_le_i32_e32 vcc, v33, v219
	v_add_u32_e32 v33, 19, v223
	s_nop 0
	v_cndmask_b32_e32 v58, v238, v58, vcc
	v_cmp_le_i32_e32 vcc, v33, v219
	v_add_u32_e32 v33, 51, v223
	s_nop 0
	v_cndmask_b32_e32 v75, v238, v75, vcc
	v_cmp_le_i32_e32 vcc, v33, v219
	v_add_u32_e32 v33, 24, v223
	s_nop 0
	v_cndmask_b32_e32 v59, v238, v59, vcc
	v_cmp_le_i32_e32 vcc, v33, v219
	v_add_u32_e32 v33, 56, v223
	s_nop 0
	v_cndmask_b32_e32 v76, v238, v76, vcc
	v_cmp_le_i32_e32 vcc, v33, v219
	v_add_u32_e32 v33, 25, v223
	s_nop 0
	v_cndmask_b32_e32 v60, v238, v60, vcc
	v_cmp_le_i32_e32 vcc, v33, v219
	v_add_u32_e32 v33, 57, v223
	s_nop 0
	v_cndmask_b32_e32 v77, v238, v77, vcc
	v_cmp_le_i32_e32 vcc, v33, v219
	v_add_u32_e32 v33, 26, v223
	s_nop 0
	v_cndmask_b32_e32 v61, v238, v61, vcc
	v_cmp_le_i32_e32 vcc, v33, v219
	v_add_u32_e32 v33, 58, v223
	s_nop 0
	v_cndmask_b32_e32 v78, v238, v78, vcc
	v_cmp_le_i32_e32 vcc, v33, v219
	v_add_u32_e32 v33, 27, v223
	s_nop 0
	v_cndmask_b32_e32 v62, v238, v62, vcc
	v_cmp_le_i32_e32 vcc, v33, v219
	v_add_u32_e32 v33, 59, v223
	s_nop 0
	v_cndmask_b32_e32 v79, v238, v79, vcc
	v_cmp_le_i32_e32 vcc, v33, v219
	s_nop 1
	v_cndmask_b32_e32 v63, v238, v63, vcc

.LBB0_179:
	ds_read_b128 v[32:35], v227
	ds_read_b128 v[84:87], v227 offset:32
	ds_read_b128 v[128:131], v227 offset:128
	ds_read_b128 v[36:39], v227 offset:160
	ds_read_b128 v[88:91], v227 offset:64
	ds_read_b128 v[92:95], v227 offset:96
	ds_read_b128 v[40:43], v227 offset:192
	ds_read_b128 v[44:47], v227 offset:224
	s_waitcnt lgkmcnt(14)
	v_mfma_f32_32x32x16_bf16 v[16:31], v[124:127], v[184:187], v[16:31]
	v_exp_f32_e32 v64, v64
	v_exp_f32_e32 v65, v65
	v_exp_f32_e32 v66, v66
	v_exp_f32_e32 v67, v67
	s_waitcnt lgkmcnt(7)
	v_pk_add_f32 v[80:81], v[32:33], v[204:205] op_sel_hi:[1,0] neg_lo:[0,1] neg_hi:[0,1]
	v_pk_add_f32 v[82:83], v[34:35], v[204:205] op_sel_hi:[1,0] neg_lo:[0,1] neg_hi:[0,1]
	s_waitcnt lgkmcnt(2)
	v_mfma_f32_32x32x16_bf16 v[0:15], v[124:127], v[156:159], v[0:15]
	v_exp_f32_e32 v68, v68
	v_exp_f32_e32 v69, v69
	v_exp_f32_e32 v70, v70
	v_exp_f32_e32 v71, v71
	v_pk_add_f32 v[84:85], v[84:85], v[204:205] op_sel_hi:[1,0] neg_lo:[0,1] neg_hi:[0,1]
	v_pk_add_f32 v[86:87], v[86:87], v[204:205] op_sel_hi:[1,0] neg_lo:[0,1] neg_hi:[0,1]
	v_add_u32_e32 v124, s24, v220
	ds_read_b128 v[156:159], v124
	ds_read_b128 v[152:155], v124 offset:512
	v_mfma_f32_32x32x16_bf16 v[16:31], v[120:123], v[176:179], v[16:31]
	v_exp_f32_e32 v72, v72
	v_exp_f32_e32 v73, v73
	v_exp_f32_e32 v74, v74
	v_exp_f32_e32 v75, v75
	v_pk_add_f32 v[88:89], v[88:89], v[204:205] op_sel_hi:[1,0] neg_lo:[0,1] neg_hi:[0,1]
	v_pk_add_f32 v[90:91], v[90:91], v[204:205] op_sel_hi:[1,0] neg_lo:[0,1] neg_hi:[0,1]
	ds_read_b128 v[148:151], v124 offset:2048
	ds_read_b128 v[144:147], v124 offset:2560
	v_mfma_f32_32x32x16_bf16 v[0:15], v[120:123], v[172:175], v[0:15]
	v_exp_f32_e32 v76, v76
	v_exp_f32_e32 v77, v77
	v_exp_f32_e32 v78, v78
	v_exp_f32_e32 v79, v79
	v_pk_add_f32 v[92:93], v[92:93], v[204:205] op_sel_hi:[1,0] neg_lo:[0,1] neg_hi:[0,1]
	v_pk_add_f32 v[94:95], v[94:95], v[204:205] op_sel_hi:[1,0] neg_lo:[0,1] neg_hi:[0,1]
	ds_read_b128 v[140:143], v124 offset:4096
	ds_read_b128 v[132:135], v124 offset:4608
	v_mfma_f32_32x32x16_bf16 v[16:31], v[112:115], v[180:183], v[16:31]
	v_exp_f32_e32 v48, v48
	v_exp_f32_e32 v49, v49
	v_exp_f32_e32 v50, v50
	v_exp_f32_e32 v51, v51
	v_pk_add_f32 v[32:33], v[128:129], v[204:205] op_sel_hi:[1,0] neg_lo:[0,1] neg_hi:[0,1]
	v_pk_add_f32 v[34:35], v[130:131], v[204:205] op_sel_hi:[1,0] neg_lo:[0,1] neg_hi:[0,1]
	s_waitcnt lgkmcnt(6)
	ds_read_b128 v[136:139], v124 offset:6144
	ds_read_b128 v[128:131], v124 offset:6656
	v_mfma_f32_32x32x16_bf16 v[0:15], v[112:115], v[168:171], v[0:15]
	v_exp_f32_e32 v52, v52
	v_exp_f32_e32 v53, v53
	v_exp_f32_e32 v54, v54
	v_exp_f32_e32 v55, v55
	v_pk_add_f32 v[36:37], v[36:37], v[204:205] op_sel_hi:[1,0] neg_lo:[0,1] neg_hi:[0,1]
	v_pk_add_f32 v[38:39], v[38:39], v[204:205] op_sel_hi:[1,0] neg_lo:[0,1] neg_hi:[0,1]
	v_mfma_f32_32x32x16_bf16 v[16:31], v[104:107], v[164:167], v[16:31]
	v_exp_f32_e32 v56, v56
	v_exp_f32_e32 v57, v57
	v_exp_f32_e32 v58, v58
	v_exp_f32_e32 v59, v59
	v_pk_add_f32 v[40:41], v[40:41], v[204:205] op_sel_hi:[1,0] neg_lo:[0,1] neg_hi:[0,1]
	v_pk_add_f32 v[42:43], v[42:43], v[204:205] op_sel_hi:[1,0] neg_lo:[0,1] neg_hi:[0,1]
	v_mfma_f32_32x32x16_bf16 v[0:15], v[104:107], v[160:163], v[0:15]
	v_exp_f32_e32 v60, v60
	v_exp_f32_e32 v61, v61
	v_exp_f32_e32 v62, v62
	v_exp_f32_e32 v63, v63
	v_pk_add_f32 v[44:45], v[44:45], v[204:205] op_sel_hi:[1,0] neg_lo:[0,1] neg_hi:[0,1]
	v_pk_add_f32 v[46:47], v[46:47], v[204:205] op_sel_hi:[1,0] neg_lo:[0,1] neg_hi:[0,1]
	s_mov_b64 s[16:17], -1
	s_and_b64 vcc, exec, s[40:41]
	s_cbranch_vccnz .LBB0_206
	s_andn2_b64 vcc, exec, s[16:17]
	s_cbranch_vccz .LBB0_211

.LBB0_183:
	v_add_u32_e32 v162, s22, v221
	ds_read_b64_tr_b16 v[188:189], v162 offset:24576
	ds_read_b64_tr_b16 v[190:191], v162 offset:25088
	v_mfma_f32_32x32x16_bf16 v[80:95], v[156:159], v[116:119], v[80:95]
	v_add_f32_e32 v104, v64, v65
	v_add_f32_e32 v104, v66, v104
	v_add_f32_e32 v104, v67, v104
	v_add_f32_e32 v104, v68, v104
	v_add_f32_e32 v104, v69, v104
	v_cvt_pk_bf16_f32 v124, v64, v65
	v_cvt_pk_bf16_f32 v125, v66, v67
	ds_read_b64_tr_b16 v[184:185], v162 offset:28672
	ds_read_b64_tr_b16 v[186:187], v162 offset:29184
	v_mfma_f32_32x32x16_bf16 v[32:47], v[152:155], v[116:119], v[32:47]
	v_add_f32_e32 v104, v70, v104
	v_add_f32_e32 v104, v71, v104
	v_add_f32_e32 v104, v72, v104
	v_add_f32_e32 v104, v73, v104
	v_cvt_pk_bf16_f32 v126, v68, v69
	v_cvt_pk_bf16_f32 v127, v70, v71
	ds_read_b64_tr_b16 v[180:181], v162 offset:25600
	ds_read_b64_tr_b16 v[182:183], v162 offset:26112
	v_mfma_f32_32x32x16_bf16 v[80:95], v[148:151], v[108:111], v[80:95]
	v_add_f32_e32 v104, v74, v104
	v_add_f32_e32 v104, v75, v104
	v_add_f32_e32 v104, v76, v104
	v_add_f32_e32 v104, v77, v104
	v_cvt_pk_bf16_f32 v120, v72, v73
	v_cvt_pk_bf16_f32 v121, v74, v75
	ds_read_b64_tr_b16 v[176:177], v162 offset:29696
	ds_read_b64_tr_b16 v[178:179], v162 offset:30208
	v_mfma_f32_32x32x16_bf16 v[32:47], v[144:147], v[108:111], v[32:47]
	v_add_f32_e32 v104, v78, v104
	v_add_f32_e32 v104, v79, v104
	v_add_f32_e32 v104, v48, v104
	v_add_f32_e32 v104, v49, v104
	v_cvt_pk_bf16_f32 v122, v76, v77
	v_cvt_pk_bf16_f32 v123, v78, v79
	ds_read_b64_tr_b16 v[172:173], v162 offset:26624
	ds_read_b64_tr_b16 v[174:175], v162 offset:27136
	v_mfma_f32_32x32x16_bf16 v[80:95], v[140:143], v[100:103], v[80:95]
	v_add_f32_e32 v104, v50, v104
	v_add_f32_e32 v104, v51, v104
	v_add_f32_e32 v104, v52, v104
	v_add_f32_e32 v104, v53, v104
	v_cvt_pk_bf16_f32 v112, v48, v49
	v_cvt_pk_bf16_f32 v113, v50, v51
	ds_read_b64_tr_b16 v[168:169], v162 offset:30720
	ds_read_b64_tr_b16 v[170:171], v162 offset:31232
	v_mfma_f32_32x32x16_bf16 v[32:47], v[132:135], v[100:103], v[32:47]
	v_add_f32_e32 v104, v54, v104
	v_add_f32_e32 v104, v55, v104
	v_add_f32_e32 v104, v56, v104
	v_add_f32_e32 v104, v57, v104
	v_cvt_pk_bf16_f32 v114, v52, v53
	v_cvt_pk_bf16_f32 v115, v54, v55
	ds_read_b64_tr_b16 v[164:165], v162 offset:27648
	ds_read_b64_tr_b16 v[166:167], v162 offset:28160
	v_mfma_f32_32x32x16_bf16 v[80:95], v[136:139], v[96:99], v[80:95]
	v_add_f32_e32 v104, v58, v104
	v_add_f32_e32 v104, v59, v104
	v_add_f32_e32 v104, v60, v104
	v_add_f32_e32 v222, v61, v104
	v_cvt_pk_bf16_f32 v104, v56, v57
	v_cvt_pk_bf16_f32 v105, v58, v59
	ds_read_b64_tr_b16 v[160:161], v162 offset:31744
	ds_read_b64_tr_b16 v[162:163], v162 offset:32256
	v_mfma_f32_32x32x16_bf16 v[32:47], v[128:131], v[96:99], v[32:47]
	v_add_f32_e32 v106, v62, v222
	v_add_f32_e32 v106, v63, v106
	v_add_f32_e32 v222, 0, v106
	v_cvt_pk_bf16_f32 v106, v60, v61
	v_cvt_pk_bf16_f32 v107, v62, v63
	s_add_i32 s78, s4, 2
	s_cmp_ge_i32 s78, s20
	s_cselect_b64 s[52:53], -1, 0
	s_and_b64 vcc, exec, s[52:53]
	s_cbranch_vccnz .LBB0_185
	s_lshl_b64 s[16:17], s[78:79], 17
	s_add_i32 s5, s24, s18
	v_lshl_add_u64 v[246:247], v[206:207], 0, s[16:17]
	s_mov_b32 m0, s5
	s_nop 0
	global_load_lds_dwordx4 v[246:247], off
.LBB0_185:
	s_add_i32 s5, s24, 0x2000
	s_cmpk_lg_i32 s24, 0x4000
	s_cselect_b32 s22, s5, 0
	s_cmp_lt_i32 s4, s20
	s_cselect_b64 s[16:17], -1, 0
	s_cmp_ge_i32 s4, s20
	s_cbranch_scc1 .LBB0_187
	s_mov_b32 s5, s79
	s_lshl_b64 s[4:5], s[4:5], 17
	s_add_i32 s36, s22, s19
	v_lshl_add_u64 v[246:247], v[208:209], 0, s[4:5]
	s_mov_b32 m0, s36
	s_nop 0
	global_load_lds_dwordx4 v[246:247], off

.LBB0_192:
	s_waitcnt lgkmcnt(14)
	v_mfma_f32_32x32x16_bf16 v[16:31], v[124:127], v[188:191], v[16:31]
	v_exp_f32_e32 v80, v80
	v_exp_f32_e32 v81, v81
	v_exp_f32_e32 v82, v82
	v_exp_f32_e32 v83, v83
	s_waitcnt lgkmcnt(7)
	v_pk_add_f32 v[64:65], v[64:65], v[204:205] op_sel_hi:[1,0] neg_lo:[0,1] neg_hi:[0,1]
	v_pk_add_f32 v[66:67], v[66:67], v[204:205] op_sel_hi:[1,0] neg_lo:[0,1] neg_hi:[0,1]
	s_waitcnt lgkmcnt(2)
	v_mfma_f32_32x32x16_bf16 v[0:15], v[124:127], v[184:187], v[0:15]
	v_exp_f32_e32 v84, v84
	v_exp_f32_e32 v85, v85
	v_exp_f32_e32 v86, v86
	v_exp_f32_e32 v87, v87
	v_pk_add_f32 v[68:69], v[68:69], v[204:205] op_sel_hi:[1,0] neg_lo:[0,1] neg_hi:[0,1]
	v_pk_add_f32 v[70:71], v[70:71], v[204:205] op_sel_hi:[1,0] neg_lo:[0,1] neg_hi:[0,1]
	s_and_b64 vcc, exec, s[4:5]
	v_add_u32_e32 v124, s22, v220
	s_cbranch_vccnz .LBB0_194
	ds_read_b128 v[156:159], v124
	ds_read_b128 v[152:155], v124 offset:512
.LBB0_194:
	v_mfma_f32_32x32x16_bf16 v[16:31], v[120:123], v[180:183], v[16:31]
	v_mov_b32_e32 v205, v204
	v_exp_f32_e32 v88, v88
	v_exp_f32_e32 v89, v89
	v_exp_f32_e32 v90, v90
	v_exp_f32_e32 v91, v91
	v_pk_add_f32 v[72:73], v[72:73], v[204:205] neg_lo:[0,1] neg_hi:[0,1]
	v_pk_add_f32 v[74:75], v[74:75], v[204:205] neg_lo:[0,1] neg_hi:[0,1]
	s_and_b64 vcc, exec, s[4:5]
	s_cbranch_vccnz .LBB0_196
	ds_read_b128 v[148:151], v124 offset:2048
	ds_read_b128 v[144:147], v124 offset:2560
.LBB0_196:
	v_mfma_f32_32x32x16_bf16 v[0:15], v[120:123], v[176:179], v[0:15]
	v_exp_f32_e32 v92, v92
	v_exp_f32_e32 v93, v93
	v_exp_f32_e32 v94, v94
	v_exp_f32_e32 v95, v95
	v_pk_add_f32 v[76:77], v[76:77], v[204:205] neg_lo:[0,1] neg_hi:[0,1]
	v_pk_add_f32 v[78:79], v[78:79], v[204:205] neg_lo:[0,1] neg_hi:[0,1]
	s_and_b64 vcc, exec, s[4:5]
	s_cbranch_vccnz .LBB0_198
	ds_read_b128 v[140:143], v124 offset:4096
	ds_read_b128 v[132:135], v124 offset:4608

.LBB0_200:
	v_mfma_f32_32x32x16_bf16 v[0:15], v[112:115], v[168:171], v[0:15]
	v_exp_f32_e32 v36, v36
	v_exp_f32_e32 v37, v37
	v_exp_f32_e32 v38, v38
	v_exp_f32_e32 v39, v39
	v_pk_add_f32 v[52:53], v[52:53], v[204:205] neg_lo:[0,1] neg_hi:[0,1]
	v_pk_add_f32 v[54:55], v[54:55], v[204:205] neg_lo:[0,1] neg_hi:[0,1]
	v_mfma_f32_32x32x16_bf16 v[16:31], v[104:107], v[164:167], v[16:31]
	v_exp_f32_e32 v40, v40
	v_exp_f32_e32 v41, v41
	v_exp_f32_e32 v42, v42
	v_exp_f32_e32 v43, v43
	v_pk_add_f32 v[56:57], v[56:57], v[204:205] neg_lo:[0,1] neg_hi:[0,1]
	v_pk_add_f32 v[58:59], v[58:59], v[204:205] neg_lo:[0,1] neg_hi:[0,1]
	v_mfma_f32_32x32x16_bf16 v[0:15], v[104:107], v[160:163], v[0:15]
	v_exp_f32_e32 v44, v44
	v_exp_f32_e32 v45, v45
	v_exp_f32_e32 v46, v46
	v_exp_f32_e32 v47, v47
	v_pk_add_f32 v[60:61], v[60:61], v[204:205] neg_lo:[0,1] neg_hi:[0,1]
	v_pk_add_f32 v[62:63], v[62:63], v[204:205] neg_lo:[0,1] neg_hi:[0,1]
	s_mov_b64 s[4:5], -1
	s_and_b64 vcc, exec, s[52:53]
	s_cbranch_vccnz .LBB0_212
	s_andn2_b64 vcc, exec, s[4:5]
	s_cbranch_vccz .LBB0_217
